# static s_setprio 1 for the second resident workgroup of each CU (blockIdx >= 256) at flash-loop entry, no per-segment flips
# speedup vs baseline: 1.0050x; 1.0050x over previous
.LBB0_850:
	s_and_b64 s[2:3], s[10:11], exec
	v_readlane_b32 s2, v251, 29
	v_readlane_b32 s3, v251, 30
	s_cselect_b32 s2, s22, 0
	v_writelane_b32 v251, s2, 29
	v_mov_b32_e32 v0, v206
	v_mov_b32_e32 v79, 0
	v_writelane_b32 v251, s3, 30
	s_cmp_gt_u32 s2, s23
	v_mov_b32_e32 v78, 0
	v_mov_b32_e32 v77, 0
	v_mov_b32_e32 v76, 0
	v_mov_b32_e32 v75, 0
	v_mov_b32_e32 v74, 0
	v_mov_b32_e32 v73, 0
	v_mov_b32_e32 v72, 0
	v_mov_b32_e32 v71, 0
	v_mov_b32_e32 v70, 0
	v_mov_b32_e32 v69, 0
	v_mov_b32_e32 v68, 0
	v_mov_b32_e32 v67, 0
	v_mov_b32_e32 v66, 0
	v_mov_b32_e32 v65, 0
	v_mov_b32_e32 v64, 0
	v_mov_b32_e32 v63, 0
	v_mov_b32_e32 v62, 0
	v_mov_b32_e32 v61, 0
	v_mov_b32_e32 v60, 0
	v_mov_b32_e32 v59, 0
	v_mov_b32_e32 v58, 0
	v_mov_b32_e32 v57, 0
	v_mov_b32_e32 v56, 0
	v_mov_b32_e32 v55, 0
	v_mov_b32_e32 v54, 0
	v_mov_b32_e32 v53, 0
	v_mov_b32_e32 v52, 0
	v_mov_b32_e32 v51, 0
	v_mov_b32_e32 v50, 0
	v_mov_b32_e32 v49, 0
	v_mov_b32_e32 v48, 0
	v_mov_b32_e32 v202, 0
	s_cbranch_scc1 .LBB0_869
	v_readlane_b32 s48, v249, 26
	s_lshl_b64 s[14:15], s[0:1], 1
	v_readlane_b32 s50, v249, 28
	v_readlane_b32 s51, v249, 29
	s_add_u32 s0, s50, s14
	s_addc_u32 s1, s51, s15
	v_ashrrev_i32_e32 v8, 4, v0
	s_add_u32 s0, s0, s6
	v_ashrrev_i32_e32 v2, 3, v0
	v_ashrrev_i32_e32 v9, 31, v8
	s_addc_u32 s1, s1, s7
	v_ashrrev_i32_e32 v3, 31, v2
	v_lshlrev_b32_e32 v1, 4, v0
	v_lshlrev_b64 v[10:11], 8, v[8:9]
	v_readlane_b32 s16, v251, 29
	s_and_b64 s[2:3], s[10:11], exec
	v_lshlrev_b64 v[4:5], 7, v[2:3]
	v_lshl_add_u64 v[12:13], s[0:1], 0, v[10:11]
	v_and_b32_e32 v14, 0xf0, v1
	v_mov_b32_e32 v15, v33
	v_readlane_b32 s17, v251, 30
	s_cselect_b32 s25, s24, -1
	v_lshl_add_u64 v[6:7], s[0:1], 0, v[4:5]
	v_lshl_add_u64 v[12:13], v[12:13], 0, v[14:15]
	s_lshl_b64 s[0:1], s[16:17], 14
	v_lshl_add_u64 v[12:13], v[12:13], 0, s[0:1]
	s_mov_b32 s2, 0x803000
	v_add_co_u32_e32 v16, vcc, s2, v12
	s_mov_b32 s2, 0x802000
	s_nop 0
	v_addc_co_u32_e32 v17, vcc, 0, v13, vcc
	v_add_co_u32_e32 v18, vcc, s2, v12
	s_mov_b32 s2, 0x801000
	s_nop 0
	v_addc_co_u32_e32 v19, vcc, 0, v13, vcc
	global_load_dwordx4 v[148:151], v[16:17], off
	global_load_dwordx4 v[152:155], v[18:19], off
	v_add_co_u32_e32 v16, vcc, s2, v12
	v_and_b32_e32 v32, 0x70, v1
	s_nop 0
	v_addc_co_u32_e32 v17, vcc, 0, v13, vcc
	s_mov_b32 s2, 0x800000
	v_lshl_add_u64 v[6:7], v[6:7], 0, v[32:33]
	v_add_co_u32_e32 v12, vcc, s2, v12
	v_lshl_add_u64 v[6:7], v[6:7], 0, s[0:1]
	s_nop 0
	v_addc_co_u32_e32 v13, vcc, 0, v13, vcc
	s_movk_i32 s2, 0x3000
	global_load_dwordx4 v[136:139], v[16:17], off
	global_load_dwordx4 v[140:143], v[12:13], off
	v_add_co_u32_e32 v12, vcc, s2, v6
	s_movk_i32 s2, 0x2000
	s_nop 0
	v_addc_co_u32_e32 v13, vcc, 0, v7, vcc
	v_add_co_u32_e32 v16, vcc, s2, v6
	s_movk_i32 s2, 0x1000
	s_nop 0
	v_addc_co_u32_e32 v17, vcc, 0, v7, vcc
	v_add_co_u32_e32 v18, vcc, s2, v6
	v_mad_u64_u32 v[188:189], s[2:3], v2, s30, v[32:33]
	s_nop 0
	v_addc_co_u32_e32 v19, vcc, 0, v7, vcc
	global_load_dwordx4 v[144:147], v[16:17], off
	global_load_dwordx4 v[132:135], v[18:19], off
	global_load_dwordx4 v[156:159], v[12:13], off
	global_load_dwordx4 v[128:131], v[6:7], off
	v_and_b32_e32 v1, 31, v0
	v_lshrrev_b32_e32 v2, 1, v0
	s_movk_i32 s2, 0x108
	v_and_b32_e32 v6, 16, v2
	v_mul_u32_u24_e32 v7, 0x90, v1
	v_lshrrev_b32_e32 v2, 3, v0
	v_mul_u32_u24_e32 v1, 0x84, v1
	v_mad_u64_u32 v[190:191], s[2:3], v8, s2, v[14:15]
	v_and_b32_e32 v8, 4, v2
	v_lshlrev_b32_e32 v1, 1, v1
	v_lshl_add_u32 v167, v8, 1, v1
	v_lshl_add_u64 v[2:3], s[0:1], 0, v[4:5]
	v_and_b32_e32 v1, 7, v0
	v_lshl_or_b32 v2, v1, 4, v2
	v_lshl_add_u64 v[192:193], s[8:9], 0, v[2:3]
	v_lshl_add_u64 v[2:3], s[0:1], 0, v[10:11]
	v_and_b32_e32 v0, 15, v0
	v_mov_b32_e32 v46, v33
	v_mov_b32_e32 v47, v33
	v_lshl_or_b32 v2, v0, 4, v2
	v_sub_u32_e32 v0, v160, v8
	s_lshl_b32 s0, s16, 7
	v_mov_b32_e32 v32, v33
	v_mov_b32_e32 v34, v33
	v_mov_b32_e32 v35, v33
	v_mov_b32_e32 v36, v33
	v_mov_b32_e32 v37, v33
	v_mov_b32_e32 v38, v33
	v_mov_b32_e32 v39, v33
	v_mov_b32_e32 v40, v33
	v_mov_b32_e32 v41, v33
	v_mov_b32_e32 v42, v33
	v_mov_b32_e32 v43, v33
	v_mov_b32_e32 v44, v33
	v_mov_b32_e32 v45, v33
	v_mov_b64_e32 v[62:63], v[46:47]
	v_mov_b64_e32 v[78:79], v[46:47]
	v_lshl_add_u64 v[194:195], s[8:9], 0, v[2:3]
	s_lshl_b32 s26, s16, 1
	v_subrev_u32_e32 v189, s0, v0
	s_or_b32 s27, s0, 0x7f
	v_mov_b32_e32 v201, 0xf149f2ca
	v_mov_b32_e32 v202, 0
	v_add_u32_e32 v191, v6, v7
	v_mov_b64_e32 v[60:61], v[44:45]
	v_mov_b64_e32 v[58:59], v[42:43]
	v_mov_b64_e32 v[56:57], v[40:41]
	v_mov_b64_e32 v[54:55], v[38:39]
	v_mov_b64_e32 v[52:53], v[36:37]
	v_mov_b64_e32 v[50:51], v[34:35]
	v_mov_b64_e32 v[48:49], v[32:33]
	v_mov_b64_e32 v[76:77], v[44:45]
	v_mov_b64_e32 v[74:75], v[42:43]
	v_mov_b64_e32 v[72:73], v[40:41]
	v_mov_b64_e32 v[70:71], v[38:39]
	v_mov_b64_e32 v[68:69], v[36:37]
	v_mov_b64_e32 v[66:67], v[34:35]
	v_mov_b64_e32 v[64:65], v[32:33]
	v_readlane_b32 s49, v249, 27
	v_readlane_b32 s52, v249, 30
	v_readlane_b32 s53, v249, 31
	v_readlane_b32 s54, v249, 32
	v_readlane_b32 s55, v249, 33
	v_readlane_b32 s56, v249, 34
	v_readlane_b32 s57, v249, 35
	v_readlane_b32 s58, v249, 36
	v_readlane_b32 s59, v249, 37
	v_readlane_b32 s60, v249, 38
	v_readlane_b32 s61, v249, 39
	v_readlane_b32 s62, v249, 40
	v_readlane_b32 s63, v249, 41
	v_readlane_b32 s0, v250, 54
	s_nop 0
	s_cmpk_lt_u32 s0, 0x400
	s_cbranch_scc1 .Lfp_skip
	s_setprio 1
